# P1 norm: x rows loaded with the default cache policy instead of non-temporal (x is read again by the FFN1 residual epilogue)
# baseline (speedup 1.0000x reference)
.LBB0_167:
	s_or_b64 exec, exec, s[10:11]
	v_lshl_add_u64 v[0:1], v[0:1], 0, v[108:109]
	global_load_dwordx4 v[92:95], v[0:1], off
	global_load_dwordx4 v[84:87], v[0:1], off offset:1024
	global_load_dwordx4 v[56:59], v[0:1], off offset:3072
	global_load_dwordx4 v[64:67], v[0:1], off offset:2048
	v_add_co_u32_e32 v2, vcc, 0x1000, v0
	v_ashrrev_i32_e32 v12, 9, v114
	s_nop 0
	v_addc_co_u32_e32 v3, vcc, 0, v1, vcc
	global_load_dwordx4 v[52:55], v[2:3], off
	global_load_dwordx4 v[48:51], v[2:3], off offset:1024
	global_load_dwordx4 v[40:43], v[2:3], off offset:3072
	global_load_dwordx4 v[44:47], v[2:3], off offset:2048
	v_lshrrev_b32_e32 v2, 6, v100
	v_add_u32_e32 v13, 8, v2
	v_add_co_u32_e32 v2, vcc, 0x2000, v0
	global_load_dwordx4 v[8:11], v[102:103], off
	global_load_dwordx4 v[4:7], v[102:103], off offset:1024
	v_addc_co_u32_e32 v3, vcc, 0, v1, vcc
	global_load_dwordx4 v[36:39], v[2:3], off
	global_load_dwordx4 v[32:35], v[2:3], off offset:1024
	global_load_dwordx4 v[28:31], v[2:3], off offset:2048
	global_load_dwordx4 v[24:27], v[2:3], off offset:3072
	v_cndmask_b32_e64 v12, v13, v12, s[2:3]
	v_add_co_u32_e32 v0, vcc, 0x3000, v0
	v_mad_i64_i32 v[12:13], s[2:3], v12, s16, v[110:111]
	s_nop 0
	v_addc_co_u32_e32 v1, vcc, 0, v1, vcc
	v_lshl_add_u64 v[76:77], v[12:13], 0, v[108:109]
	global_load_dwordx4 v[20:23], v[0:1], off
	global_load_dwordx4 v[16:19], v[0:1], off offset:1024
	global_load_dwordx4 v[12:15], v[0:1], off offset:2048
	s_nop 0
	global_load_dwordx4 v[0:3], v[0:1], off offset:3072
	v_add_co_u32_e32 v60, vcc, s14, v76
	v_lshl_add_u64 v[112:113], v[76:77], 0, s[8:9]
	s_nop 0
	v_addc_co_u32_e32 v61, vcc, 0, v77, vcc
	global_load_dwordx4 v[96:99], v[60:61], off
	v_add_u32_e32 v114, s12, v114
	s_waitcnt vmcnt(18)
	v_pk_mul_f32 v[60:61], v[94:95], v[94:95]
	v_pk_mul_f32 v[62:63], v[92:93], v[92:93]
	s_waitcnt vmcnt(17)
	v_pk_mul_f32 v[68:69], v[86:87], v[86:87]
	v_pk_mul_f32 v[70:71], v[84:85], v[84:85]
	v_pk_mov_b32 v[78:79], v[62:63], v[60:61] op_sel:[1,0]
	v_mov_b32_e32 v63, v61
	v_pk_mov_b32 v[60:61], v[70:71], v[68:69] op_sel:[1,0]
	v_mov_b32_e32 v71, v69
	s_waitcnt vmcnt(16)
	v_mul_f32_e32 v75, v58, v58
	s_waitcnt vmcnt(15)
	v_mul_f32_e32 v72, v65, v65
	v_mul_f32_e32 v74, v67, v67
	v_pk_add_f32 v[62:63], v[78:79], v[62:63]
	v_pk_add_f32 v[60:61], v[60:61], v[70:71]
	v_mul_f32_e32 v82, v56, v56
	v_mul_f32_e32 v83, v57, v57
	v_mul_f32_e32 v80, v59, v59
	v_pk_fma_f32 v[68:69], v[64:65], v[64:65], v[72:73] op_sel_hi:[1,1,0]
	v_pk_fma_f32 v[72:73], v[66:67], v[66:67], v[74:75] op_sel_hi:[1,1,0]
	v_pk_add_f32 v[62:63], v[62:63], v[62:63] op_sel:[0,1] op_sel_hi:[1,0]
	v_pk_add_f32 v[60:61], v[60:61], v[60:61] op_sel:[0,1] op_sel_hi:[1,0]
	v_mov_b32_e32 v69, v75
	v_mov_b32_e32 v73, v80
	s_waitcnt vmcnt(14)
	v_pk_mul_f32 v[70:71], v[54:55], v[54:55]
	v_pk_mul_f32 v[74:75], v[52:53], v[52:53]
	s_waitcnt vmcnt(13)
	v_pk_mul_f32 v[78:79], v[50:51], v[50:51]
	v_pk_mul_f32 v[80:81], v[48:49], v[48:49]
	v_mov_b32_e32 v63, v82
	v_mov_b32_e32 v61, v83
	v_pk_add_f32 v[68:69], v[68:69], v[72:73]
	v_pk_mov_b32 v[72:73], v[74:75], v[70:71] op_sel:[1,0]
	v_mov_b32_e32 v75, v71
	v_pk_mov_b32 v[70:71], v[80:81], v[78:79] op_sel:[1,0]
	v_mov_b32_e32 v81, v79
	v_pk_add_f32 v[60:61], v[62:63], v[60:61]
	v_pk_add_f32 v[72:73], v[72:73], v[74:75]
	v_pk_add_f32 v[70:71], v[70:71], v[80:81]
	v_pk_add_f32 v[60:61], v[60:61], v[68:69]
	s_waitcnt vmcnt(12)
	v_mul_f32_e32 v88, v40, v40
	v_mul_f32_e32 v89, v41, v41
	v_add_f32_e32 v74, v60, v61
	v_pk_add_f32 v[60:61], v[72:73], v[72:73] op_sel:[0,1] op_sel_hi:[1,0]
	v_pk_add_f32 v[62:63], v[70:71], v[70:71] op_sel:[0,1] op_sel_hi:[1,0]
	v_mov_b32_e32 v61, v88
	v_mov_b32_e32 v63, v89
	v_pk_add_f32 v[60:61], v[60:61], v[62:63]
	s_waitcnt vmcnt(11)
	v_mul_f32_e32 v62, v45, v45
	v_mul_f32_e32 v68, v47, v47
	v_mul_f32_e32 v90, v42, v42
	v_mul_f32_e32 v75, v43, v43
	v_pk_fma_f32 v[62:63], v[44:45], v[44:45], v[62:63] op_sel_hi:[1,1,0]
	v_pk_fma_f32 v[68:69], v[46:47], v[46:47], v[68:69] op_sel_hi:[1,1,0]
	v_mov_b32_e32 v63, v90
	v_mov_b32_e32 v69, v75
	v_pk_add_f32 v[62:63], v[62:63], v[68:69]
	s_nop 0
	v_pk_add_f32 v[60:61], v[60:61], v[62:63]
	s_waitcnt vmcnt(8)
	v_pk_mul_f32 v[62:63], v[36:37], v[36:37]
	v_add_f32_e32 v78, v60, v61
	v_pk_mul_f32 v[60:61], v[38:39], v[38:39]
	s_nop 0
	v_pk_mov_b32 v[68:69], v[62:63], v[60:61] op_sel:[1,0]
	v_mov_b32_e32 v63, v61
	v_pk_add_f32 v[60:61], v[68:69], v[62:63]
	s_waitcnt vmcnt(7)
	v_pk_mul_f32 v[62:63], v[34:35], v[34:35]
	v_pk_mul_f32 v[68:69], v[32:33], v[32:33]
	v_pk_add_f32 v[60:61], v[60:61], v[60:61] op_sel:[0,1] op_sel_hi:[1,0]
	v_pk_mov_b32 v[70:71], v[68:69], v[62:63] op_sel:[1,0]
	v_mov_b32_e32 v69, v63
	v_pk_add_f32 v[62:63], v[70:71], v[68:69]
	s_waitcnt vmcnt(5)
	v_mul_f32_e32 v68, v24, v24
	v_mul_f32_e32 v69, v25, v25
	v_pk_add_f32 v[62:63], v[62:63], v[62:63] op_sel:[0,1] op_sel_hi:[1,0]
	v_mov_b32_e32 v61, v68
	v_mov_b32_e32 v63, v69
	v_pk_add_f32 v[60:61], v[60:61], v[62:63]
	v_mul_f32_e32 v62, v29, v29
	v_mul_f32_e32 v68, v31, v31
	v_mul_f32_e32 v70, v26, v26
	v_mul_f32_e32 v71, v27, v27
	v_pk_fma_f32 v[62:63], v[28:29], v[28:29], v[62:63] op_sel_hi:[1,1,0]
	v_pk_fma_f32 v[68:69], v[30:31], v[30:31], v[68:69] op_sel_hi:[1,1,0]
	v_mov_b32_e32 v63, v70
	v_mov_b32_e32 v69, v71
	v_pk_add_f32 v[62:63], v[62:63], v[68:69]
	s_nop 0
	v_pk_add_f32 v[60:61], v[60:61], v[62:63]
	s_waitcnt vmcnt(4)
	v_pk_mul_f32 v[62:63], v[20:21], v[20:21]
	v_add_f32_e32 v79, v60, v61
	v_pk_mul_f32 v[60:61], v[22:23], v[22:23]
	s_nop 0
	v_pk_mov_b32 v[68:69], v[62:63], v[60:61] op_sel:[1,0]
	v_mov_b32_e32 v63, v61
	v_pk_add_f32 v[60:61], v[68:69], v[62:63]
	s_waitcnt vmcnt(3)
	v_pk_mul_f32 v[62:63], v[18:19], v[18:19]
	v_pk_mul_f32 v[68:69], v[16:17], v[16:17]
	v_pk_add_f32 v[60:61], v[60:61], v[60:61] op_sel:[0,1] op_sel_hi:[1,0]
	v_pk_mov_b32 v[70:71], v[68:69], v[62:63] op_sel:[1,0]
	v_mov_b32_e32 v69, v63
	v_pk_add_f32 v[62:63], v[70:71], v[68:69]
	s_waitcnt vmcnt(1)
	v_mul_f32_e32 v68, v0, v0
	v_mul_f32_e32 v69, v1, v1
	v_pk_add_f32 v[62:63], v[62:63], v[62:63] op_sel:[0,1] op_sel_hi:[1,0]
	v_mov_b32_e32 v61, v68
	v_mov_b32_e32 v63, v69
	v_pk_add_f32 v[60:61], v[60:61], v[62:63]
	v_mul_f32_e32 v62, v13, v13
	v_mul_f32_e32 v70, v2, v2
	v_pk_fma_f32 v[62:63], v[12:13], v[12:13], v[62:63] op_sel_hi:[1,1,0]
	v_mul_f32_e32 v68, v15, v15
	v_mov_b32_e32 v63, v70
	ds_bpermute_b32 v70, v115, v74
	v_mul_f32_e32 v71, v3, v3
	v_pk_fma_f32 v[68:69], v[14:15], v[14:15], v[68:69] op_sel_hi:[1,1,0]
	s_nop 0
	v_mov_b32_e32 v69, v71
	v_pk_add_f32 v[62:63], v[62:63], v[68:69]
	s_waitcnt lgkmcnt(0)
	v_add_f32_e32 v69, v74, v70
	v_pk_add_f32 v[60:61], v[60:61], v[62:63]
	ds_bpermute_b32 v70, v115, v78
	v_add_f32_e32 v68, v60, v61
	ds_bpermute_b32 v71, v115, v79
	ds_bpermute_b32 v80, v115, v68
	ds_bpermute_b32 v81, v116, v69
	s_waitcnt lgkmcnt(3)
	v_add_f32_e32 v70, v78, v70
	ds_bpermute_b32 v78, v116, v70
	s_waitcnt lgkmcnt(3)
	v_add_f32_e32 v71, v79, v71
	s_waitcnt lgkmcnt(2)
	v_add_f32_e32 v68, v68, v80
	s_waitcnt lgkmcnt(1)
	v_add_f32_e32 v69, v69, v81
	ds_bpermute_b32 v79, v116, v71
	ds_bpermute_b32 v80, v116, v68
	ds_bpermute_b32 v81, v117, v69
	global_load_dwordx4 v[72:75], v[76:77], off
	global_load_dwordx4 v[60:63], v[76:77], off offset:1024
	s_waitcnt lgkmcnt(3)
	v_add_f32_e32 v78, v70, v78
	s_waitcnt lgkmcnt(2)
	v_add_f32_e32 v79, v71, v79
	s_waitcnt lgkmcnt(1)
	v_add_f32_e32 v88, v68, v80
	s_waitcnt lgkmcnt(0)
	v_add_f32_e32 v89, v69, v81
	ds_bpermute_b32 v90, v117, v78
	ds_bpermute_b32 v91, v117, v79
	ds_bpermute_b32 v100, v117, v88
	ds_bpermute_b32 v123, v118, v89
	global_load_dwordx4 v[124:127], v[112:113], off offset:1024
	global_load_dwordx4 v[128:131], v[112:113], off offset:2048
	global_load_dwordx4 v[80:83], v[102:103], off offset:2048
	global_load_dwordx4 v[68:71], v[102:103], off offset:3072
	s_waitcnt lgkmcnt(3)
	v_add_f32_e32 v132, v78, v90
	s_waitcnt lgkmcnt(2)
	v_add_f32_e32 v133, v79, v91
	s_waitcnt lgkmcnt(1)
	v_add_f32_e32 v100, v88, v100
	s_waitcnt lgkmcnt(0)
	v_add_f32_e32 v123, v89, v123
	global_load_dwordx4 v[88:91], v[76:77], off offset:2048
	s_nop 0
	global_load_dwordx4 v[76:79], v[76:77], off offset:3072
	ds_bpermute_b32 v134, v118, v132
	ds_bpermute_b32 v135, v118, v133
	ds_bpermute_b32 v137, v119, v123
	ds_bpermute_b32 v136, v118, v100
	s_waitcnt lgkmcnt(3)
	v_add_f32_e32 v138, v132, v134
	s_waitcnt lgkmcnt(2)
	v_add_f32_e32 v139, v133, v135
	global_load_dwordx4 v[132:135], v[112:113], off offset:3072
	s_waitcnt lgkmcnt(1)
	v_add_f32_e32 v123, v123, v137
	ds_bpermute_b32 v141, v120, v123
	s_waitcnt lgkmcnt(1)
	v_add_f32_e32 v100, v100, v136
	ds_bpermute_b32 v136, v119, v138
	ds_bpermute_b32 v140, v119, v100
	ds_bpermute_b32 v137, v119, v139
	s_waitcnt lgkmcnt(3)
	v_add_f32_e32 v123, v123, v141
	v_fmamk_f32 v123, v123, 0x3a800000, v121
	s_waitcnt lgkmcnt(2)
	v_add_f32_e32 v112, v138, v136
	v_mul_f32_e32 v136, 0x4f800000, v123
	v_cmp_gt_f32_e32 vcc, s17, v123
	s_waitcnt lgkmcnt(1)
	v_add_f32_e32 v100, v100, v140
	s_waitcnt lgkmcnt(0)
	v_add_f32_e32 v113, v139, v137
	v_cndmask_b32_e32 v123, v123, v136, vcc
	v_sqrt_f32_e32 v136, v123
	ds_bpermute_b32 v139, v120, v100
	ds_bpermute_b32 v137, v120, v112
	ds_bpermute_b32 v138, v120, v113
	v_add_u32_e32 v140, -1, v136
	v_fma_f32 v141, -v140, v136, v123
	v_cmp_ge_f32_e64 s[2:3], 0, v141
	v_add_u32_e32 v141, 1, v136
	s_waitcnt lgkmcnt(2)
	v_add_f32_e32 v143, v100, v139
	v_cndmask_b32_e64 v140, v136, v140, s[2:3]
	v_fma_f32 v136, -v141, v136, v123
	v_cmp_lt_f32_e64 s[2:3], 0, v136
	s_waitcnt lgkmcnt(0)
	v_add_f32_e32 v142, v113, v138
	v_cndmask_b32_e64 v136, v140, v141, s[2:3]
	v_mul_f32_e32 v140, 0x37800000, v136
	v_cndmask_b32_e32 v136, v136, v140, vcc
	v_cmp_class_f32_e32 vcc, v123, v122
	v_add_f32_e32 v141, v112, v137
	s_nop 0
	v_cndmask_b32_e32 v123, v136, v123, vcc
	v_div_scale_f32 v136, s[2:3], v123, v123, 1.0
	v_rcp_f32_e32 v140, v136
	s_nop 0
	v_fma_f32 v100, -v136, v140, 1.0
	v_fmac_f32_e32 v140, v100, v140
	v_div_scale_f32 v100, vcc, 1.0, v123, 1.0
	v_mul_f32_e32 v112, v100, v140
	v_fma_f32 v113, -v136, v112, v100
	v_fmac_f32_e32 v112, v113, v140
	v_fma_f32 v100, -v136, v112, v100
	v_div_fmas_f32 v100, v100, v140, v112
	v_div_fixup_f32 v100, v100, v123, 1.0
	v_pk_mul_f32 v[94:95], v[94:95], v[100:101] op_sel_hi:[1,0]
	v_pk_mul_f32 v[92:93], v[92:93], v[100:101] op_sel_hi:[1,0]
	v_pk_mul_f32 v[138:139], v[10:11], v[94:95]
	v_pk_mul_f32 v[136:137], v[8:9], v[92:93]
	s_waitcnt vmcnt(9)
	v_pk_add_f32 v[92:93], v[98:99], 1.0 op_sel_hi:[1,0]
	v_pk_add_f32 v[94:95], v[96:97], 1.0 op_sel_hi:[1,0]
	v_lshlrev_b64 v[112:113], 11, v[106:107]
	s_waitcnt vmcnt(8)
	v_pk_fma_f32 v[96:97], v[92:93], v[138:139], v[74:75]
	v_pk_fma_f32 v[98:99], v[94:95], v[136:137], v[72:73]
	v_lshl_add_u64 v[112:113], v[104:105], 0, v[112:113]
	v_cvt_pk_bf16_f32 v98, v98, v99
	v_cvt_pk_bf16_f32 v99, v96, v97
	v_pk_mul_f32 v[86:87], v[86:87], v[100:101] op_sel_hi:[1,0]
	v_pk_mul_f32 v[84:85], v[84:85], v[100:101] op_sel_hi:[1,0]
	global_store_dwordx2 v[112:113], v[98:99], off
	v_pk_mul_f32 v[96:97], v[4:5], v[84:85]
	v_pk_mul_f32 v[98:99], v[6:7], v[86:87]
	s_waitcnt vmcnt(7)
	v_pk_add_f32 v[84:85], v[126:127], 1.0 op_sel_hi:[1,0]
	v_pk_add_f32 v[86:87], v[124:125], 1.0 op_sel_hi:[1,0]
	v_pk_fma_f32 v[98:99], v[84:85], v[98:99], v[62:63]
	v_pk_fma_f32 v[96:97], v[86:87], v[96:97], v[60:61]
	v_pk_mul_f32 v[66:67], v[66:67], v[100:101] op_sel_hi:[1,0]
	v_cvt_pk_bf16_f32 v96, v96, v97
	v_cvt_pk_bf16_f32 v97, v98, v99
	v_pk_mul_f32 v[64:65], v[64:65], v[100:101] op_sel_hi:[1,0]
	global_store_dwordx2 v[112:113], v[96:97], off offset:512
	s_waitcnt vmcnt(6)
	v_pk_mul_f32 v[96:97], v[80:81], v[64:65]
	v_pk_mul_f32 v[98:99], v[82:83], v[66:67]
	v_pk_add_f32 v[64:65], v[130:131], 1.0 op_sel_hi:[1,0]
	v_pk_add_f32 v[66:67], v[128:129], 1.0 op_sel_hi:[1,0]
	s_waitcnt vmcnt(4)
	v_pk_fma_f32 v[98:99], v[64:65], v[98:99], v[90:91]
	v_pk_fma_f32 v[96:97], v[66:67], v[96:97], v[88:89]
	v_pk_mul_f32 v[58:59], v[58:59], v[100:101] op_sel_hi:[1,0]
	v_cvt_pk_bf16_f32 v96, v96, v97
	v_cvt_pk_bf16_f32 v97, v98, v99
	v_pk_mul_f32 v[98:99], v[70:71], v[58:59]
	v_fmamk_f32 v58, v141, 0x3a800000, v121
	v_mul_f32_e32 v59, 0x4f800000, v58
	v_cmp_gt_f32_e32 vcc, s17, v58
	v_pk_mul_f32 v[56:57], v[56:57], v[100:101] op_sel_hi:[1,0]
	global_store_dwordx2 v[112:113], v[96:97], off offset:1024
	v_cndmask_b32_e32 v100, v58, v59, vcc
	v_sqrt_f32_e32 v107, v100
	v_pk_mul_f32 v[96:97], v[68:69], v[56:57]
	s_waitcnt vmcnt(3)
	v_pk_add_f32 v[56:57], v[134:135], 1.0 op_sel_hi:[1,0]
	v_pk_add_f32 v[58:59], v[132:133], 1.0 op_sel_hi:[1,0]
	v_add_u32_e32 v123, -1, v107
	v_fma_f32 v124, -v123, v107, v100
	v_cmp_ge_f32_e64 s[2:3], 0, v124
	v_add_u32_e32 v124, 1, v107
	v_pk_fma_f32 v[98:99], v[56:57], v[98:99], v[78:79]
	v_cndmask_b32_e64 v123, v107, v123, s[2:3]
	v_fma_f32 v107, -v124, v107, v100
	v_cmp_lt_f32_e64 s[2:3], 0, v107
	v_pk_fma_f32 v[96:97], v[58:59], v[96:97], v[76:77]
	s_nop 0
	v_cndmask_b32_e64 v107, v123, v124, s[2:3]
	v_mul_f32_e32 v123, 0x37800000, v107
	v_cndmask_b32_e32 v107, v107, v123, vcc
	v_cmp_class_f32_e32 vcc, v100, v122
	v_cvt_pk_bf16_f32 v96, v96, v97
	v_cvt_pk_bf16_f32 v97, v98, v99
	v_cndmask_b32_e32 v100, v107, v100, vcc
	v_div_scale_f32 v107, s[2:3], v100, v100, 1.0
	v_rcp_f32_e32 v123, v107
	global_store_dwordx2 v[112:113], v[96:97], off offset:1536
	v_fma_f32 v96, -v107, v123, 1.0
	v_fmac_f32_e32 v123, v96, v123
	v_div_scale_f32 v96, vcc, 1.0, v100, 1.0
	v_mul_f32_e32 v97, v96, v123
	v_fma_f32 v98, -v107, v97, v96
	v_fmac_f32_e32 v97, v98, v123
	v_fma_f32 v96, -v107, v97, v96
	v_div_fmas_f32 v96, v96, v123, v97
	v_div_fixup_f32 v96, v96, v100, 1.0
	v_add_u32_e32 v98, 1, v106
	v_pk_mul_f32 v[46:47], v[46:47], v[96:97] op_sel_hi:[1,0]
	v_pk_mul_f32 v[44:45], v[44:45], v[96:97] op_sel_hi:[1,0]
	v_ashrrev_i32_e32 v99, 31, v98
	v_pk_mul_f32 v[44:45], v[80:81], v[44:45]
	v_pk_mul_f32 v[46:47], v[82:83], v[46:47]
	v_lshlrev_b64 v[98:99], 11, v[98:99]
	v_pk_fma_f32 v[46:47], v[64:65], v[46:47], v[90:91]
	v_pk_fma_f32 v[44:45], v[66:67], v[44:45], v[88:89]
	v_lshl_add_u64 v[98:99], v[104:105], 0, v[98:99]
	v_cvt_pk_bf16_f32 v44, v44, v45
	v_cvt_pk_bf16_f32 v45, v46, v47
	global_store_dwordx2 v[98:99], v[44:45], off offset:1024
	v_fmamk_f32 v44, v142, 0x3a800000, v121
	v_mul_f32_e32 v45, 0x4f800000, v44
	v_cmp_gt_f32_e32 vcc, s17, v44
	v_pk_mul_f32 v[42:43], v[42:43], v[96:97] op_sel_hi:[1,0]
	v_pk_mul_f32 v[40:41], v[40:41], v[96:97] op_sel_hi:[1,0]
	v_cndmask_b32_e32 v44, v44, v45, vcc
	v_sqrt_f32_e32 v45, v44
	v_pk_mul_f32 v[40:41], v[68:69], v[40:41]
	v_pk_mul_f32 v[42:43], v[70:71], v[42:43]
	v_pk_fma_f32 v[40:41], v[58:59], v[40:41], v[76:77]
	v_add_u32_e32 v46, -1, v45
	v_fma_f32 v47, -v46, v45, v44
	v_cmp_ge_f32_e64 s[2:3], 0, v47
	v_add_u32_e32 v47, 1, v45
	v_pk_fma_f32 v[42:43], v[56:57], v[42:43], v[78:79]
	v_cndmask_b32_e64 v46, v45, v46, s[2:3]
	v_fma_f32 v45, -v47, v45, v44
	v_cmp_lt_f32_e64 s[2:3], 0, v45
	v_cvt_pk_bf16_f32 v40, v40, v41
	v_cvt_pk_bf16_f32 v41, v42, v43
	v_cndmask_b32_e64 v45, v46, v47, s[2:3]
	v_mul_f32_e32 v46, 0x37800000, v45
	v_cndmask_b32_e32 v45, v45, v46, vcc
	v_cmp_class_f32_e32 vcc, v44, v122
	global_store_dwordx2 v[98:99], v[40:41], off offset:1536
	v_pk_mul_f32 v[54:55], v[54:55], v[96:97] op_sel_hi:[1,0]
	v_cndmask_b32_e32 v44, v45, v44, vcc
	v_div_scale_f32 v45, s[2:3], v44, v44, 1.0
	v_rcp_f32_e32 v46, v45
	v_pk_mul_f32 v[52:53], v[52:53], v[96:97] op_sel_hi:[1,0]
	v_pk_mul_f32 v[54:55], v[10:11], v[54:55]
	v_pk_mul_f32 v[52:53], v[8:9], v[52:53]
	v_fma_f32 v40, -v45, v46, 1.0
	v_fmac_f32_e32 v46, v40, v46
	v_div_scale_f32 v40, vcc, 1.0, v44, 1.0
	v_mul_f32_e32 v41, v40, v46
	v_fma_f32 v42, -v45, v41, v40
	v_fmac_f32_e32 v41, v42, v46
	v_fma_f32 v40, -v45, v41, v40
	v_div_fmas_f32 v40, v40, v46, v41
	v_div_fixup_f32 v40, v40, v44, 1.0
	v_add_u32_e32 v42, 2, v106
	v_pk_mul_f32 v[30:31], v[30:31], v[40:41] op_sel_hi:[1,0]
	v_pk_mul_f32 v[28:29], v[28:29], v[40:41] op_sel_hi:[1,0]
	v_ashrrev_i32_e32 v43, 31, v42
	v_pk_mul_f32 v[28:29], v[80:81], v[28:29]
	v_pk_mul_f32 v[30:31], v[82:83], v[30:31]
	v_lshlrev_b64 v[42:43], 11, v[42:43]
	v_pk_fma_f32 v[30:31], v[64:65], v[30:31], v[90:91]
	v_pk_fma_f32 v[28:29], v[66:67], v[28:29], v[88:89]
	v_lshl_add_u64 v[42:43], v[104:105], 0, v[42:43]
	v_cvt_pk_bf16_f32 v28, v28, v29
	v_cvt_pk_bf16_f32 v29, v30, v31
	global_store_dwordx2 v[42:43], v[28:29], off offset:1024
	v_fmamk_f32 v28, v143, 0x3a800000, v121
	v_mul_f32_e32 v29, 0x4f800000, v28
	v_cmp_gt_f32_e32 vcc, s17, v28
	v_pk_mul_f32 v[26:27], v[26:27], v[40:41] op_sel_hi:[1,0]
	v_pk_mul_f32 v[24:25], v[24:25], v[40:41] op_sel_hi:[1,0]
	v_cndmask_b32_e32 v28, v28, v29, vcc
	v_sqrt_f32_e32 v29, v28
	v_pk_mul_f32 v[24:25], v[68:69], v[24:25]
	v_pk_mul_f32 v[26:27], v[70:71], v[26:27]
	v_pk_fma_f32 v[24:25], v[58:59], v[24:25], v[76:77]
	v_add_u32_e32 v30, -1, v29
	v_fma_f32 v31, -v30, v29, v28
	v_cmp_ge_f32_e64 s[2:3], 0, v31
	v_add_u32_e32 v31, 1, v29
	v_pk_fma_f32 v[26:27], v[56:57], v[26:27], v[78:79]
	v_cndmask_b32_e64 v30, v29, v30, s[2:3]
	v_fma_f32 v29, -v31, v29, v28
	v_cmp_lt_f32_e64 s[2:3], 0, v29
	v_cvt_pk_bf16_f32 v24, v24, v25
	v_cvt_pk_bf16_f32 v25, v26, v27
	v_cndmask_b32_e64 v29, v30, v31, s[2:3]
	v_mul_f32_e32 v30, 0x37800000, v29
	v_cndmask_b32_e32 v29, v29, v30, vcc
	v_cmp_class_f32_e32 vcc, v28, v122
	global_store_dwordx2 v[42:43], v[24:25], off offset:1536
	v_pk_mul_f32 v[38:39], v[38:39], v[40:41] op_sel_hi:[1,0]
	v_cndmask_b32_e32 v28, v29, v28, vcc
	v_div_scale_f32 v29, s[2:3], v28, v28, 1.0
	v_rcp_f32_e32 v30, v29
	v_pk_mul_f32 v[36:37], v[36:37], v[40:41] op_sel_hi:[1,0]
	v_pk_mul_f32 v[38:39], v[10:11], v[38:39]
	v_pk_mul_f32 v[36:37], v[8:9], v[36:37]
	v_fma_f32 v24, -v29, v30, 1.0
	v_fmac_f32_e32 v30, v24, v30
	v_div_scale_f32 v24, vcc, 1.0, v28, 1.0
	v_mul_f32_e32 v25, v24, v30
	v_fma_f32 v26, -v29, v25, v24
	v_fmac_f32_e32 v25, v26, v30
	v_fma_f32 v24, -v29, v25, v24
	v_div_fmas_f32 v24, v24, v30, v25
	v_div_fixup_f32 v24, v24, v28, 1.0
	v_add_u32_e32 v26, 3, v106
	v_pk_mul_f32 v[22:23], v[22:23], v[24:25] op_sel_hi:[1,0]
	v_pk_mul_f32 v[20:21], v[20:21], v[24:25] op_sel_hi:[1,0]
	v_ashrrev_i32_e32 v27, 31, v26
	v_pk_mul_f32 v[8:9], v[8:9], v[20:21]
	v_pk_mul_f32 v[10:11], v[10:11], v[22:23]
	v_lshlrev_b64 v[26:27], 11, v[26:27]
	v_pk_fma_f32 v[10:11], v[92:93], v[10:11], v[74:75]
	v_pk_fma_f32 v[8:9], v[94:95], v[8:9], v[72:73]
	v_lshl_add_u64 v[26:27], v[104:105], 0, v[26:27]
	v_cvt_pk_bf16_f32 v8, v8, v9
	v_cvt_pk_bf16_f32 v9, v10, v11
	v_pk_mul_f32 v[50:51], v[50:51], v[96:97] op_sel_hi:[1,0]
	v_pk_mul_f32 v[48:49], v[48:49], v[96:97] op_sel_hi:[1,0]
	v_pk_mul_f32 v[34:35], v[34:35], v[40:41] op_sel_hi:[1,0]
	v_pk_mul_f32 v[32:33], v[32:33], v[40:41] op_sel_hi:[1,0]
	global_store_dwordx2 v[26:27], v[8:9], off
	v_pk_mul_f32 v[8:9], v[18:19], v[24:25] op_sel_hi:[1,0]
	v_pk_mul_f32 v[10:11], v[16:17], v[24:25] op_sel_hi:[1,0]
	v_pk_mul_f32 v[48:49], v[4:5], v[48:49]
	v_pk_mul_f32 v[50:51], v[6:7], v[50:51]
	v_pk_mul_f32 v[32:33], v[4:5], v[32:33]
	v_pk_mul_f32 v[34:35], v[6:7], v[34:35]
	v_pk_mul_f32 v[4:5], v[4:5], v[10:11]
	v_pk_mul_f32 v[6:7], v[6:7], v[8:9]
	v_pk_fma_f32 v[4:5], v[86:87], v[4:5], v[60:61]
	v_pk_fma_f32 v[6:7], v[84:85], v[6:7], v[62:63]
	v_cvt_pk_bf16_f32 v4, v4, v5
	v_cvt_pk_bf16_f32 v5, v6, v7
	global_store_dwordx2 v[26:27], v[4:5], off offset:512
	v_pk_mul_f32 v[4:5], v[14:15], v[24:25] op_sel_hi:[1,0]
	v_pk_mul_f32 v[6:7], v[12:13], v[24:25] op_sel_hi:[1,0]
	v_pk_mul_f32 v[2:3], v[2:3], v[24:25] op_sel_hi:[1,0]
	v_pk_mul_f32 v[0:1], v[0:1], v[24:25] op_sel_hi:[1,0]
	v_pk_mul_f32 v[6:7], v[80:81], v[6:7]
	v_pk_mul_f32 v[4:5], v[82:83], v[4:5]
	v_pk_mul_f32 v[0:1], v[68:69], v[0:1]
	v_pk_mul_f32 v[2:3], v[70:71], v[2:3]
	v_pk_fma_f32 v[54:55], v[92:93], v[54:55], v[74:75]
	v_pk_fma_f32 v[52:53], v[94:95], v[52:53], v[72:73]
	v_pk_fma_f32 v[50:51], v[84:85], v[50:51], v[62:63]
	v_pk_fma_f32 v[48:49], v[86:87], v[48:49], v[60:61]
	v_pk_fma_f32 v[38:39], v[92:93], v[38:39], v[74:75]
	v_pk_fma_f32 v[36:37], v[94:95], v[36:37], v[72:73]
	v_pk_fma_f32 v[34:35], v[84:85], v[34:35], v[62:63]
	v_pk_fma_f32 v[32:33], v[86:87], v[32:33], v[60:61]
	v_pk_fma_f32 v[4:5], v[64:65], v[4:5], v[90:91]
	v_pk_fma_f32 v[6:7], v[66:67], v[6:7], v[88:89]
	v_pk_fma_f32 v[2:3], v[56:57], v[2:3], v[78:79]
	v_pk_fma_f32 v[0:1], v[58:59], v[0:1], v[76:77]
	v_cmp_lt_i32_e32 vcc, s18, v114
	v_cvt_pk_bf16_f32 v52, v52, v53
	v_cvt_pk_bf16_f32 v53, v54, v55
	v_cvt_pk_bf16_f32 v48, v48, v49
	v_cvt_pk_bf16_f32 v49, v50, v51
	v_cvt_pk_bf16_f32 v36, v36, v37
	v_cvt_pk_bf16_f32 v37, v38, v39
	v_cvt_pk_bf16_f32 v32, v32, v33
	v_cvt_pk_bf16_f32 v33, v34, v35
	v_cvt_pk_bf16_f32 v6, v6, v7
	v_cvt_pk_bf16_f32 v7, v4, v5
	v_cvt_pk_bf16_f32 v0, v0, v1
	v_cvt_pk_bf16_f32 v1, v2, v3
	s_or_b64 s[6:7], vcc, s[6:7]
	v_add_u32_e32 v106, s13, v106
	global_store_dwordx2 v[98:99], v[52:53], off
	global_store_dwordx2 v[98:99], v[48:49], off offset:512
	global_store_dwordx2 v[42:43], v[36:37], off
	global_store_dwordx2 v[42:43], v[32:33], off offset:512
	global_store_dwordx2 v[26:27], v[6:7], off offset:1024
	global_store_dwordx2 v[26:27], v[0:1], off offset:1536
	s_andn2_b64 exec, exec, s[6:7]
	s_cbranch_execz .LBB0_172
